# weight-image transpose/convert jobs run through one software-pipelined loop (next job's loads in flight, two LDS tiles, one barrier per job)
# baseline (speedup 1.0000x reference)
.LBB0_43:
	s_cmpk_lt_i32 s2, 0xab0
	s_cselect_b64 s[0:1], -1, 0
	s_mov_b64 s[18:19], s[38:39]
	v_writelane_b32 v254, s0, 63
	s_cmpk_gt_i32 s2, 0xaaf
	s_nop 0
	v_writelane_b32 v255, s1, 0
	s_barrier
	s_cbranch_scc1 .LBB0_72
	s_load_dwordx2 s[12:13], s[18:19], 0xc0
	s_load_dwordx4 s[4:7], s[18:19], 0x30
	s_load_dwordx2 s[14:15], s[18:19], 0x60
	s_load_dwordx2 s[16:17], s[18:19], 0x70
	s_load_dwordx4 s[8:11], s[18:19], 0xa0
	s_waitcnt lgkmcnt(0)
	s_add_u32 s3, s12, 0x1080000
	s_addc_u32 s33, s13, 0
	s_add_u32 s18, s12, 0x1380000
	s_addc_u32 s19, s13, 0
	s_add_u32 s20, s12, 0x1580000
	s_addc_u32 s21, s13, 0
	s_add_u32 s22, s12, 0x1590000
	s_addc_u32 s23, s13, 0
	s_mov_b32 s25, 0
	v_mov_b32_e32 v3, 0
	s_movk_i32 s36, 0x104
	s_mov_b32 s37, 0x8200
	s_movk_i32 s43, 0x800
	s_movk_i32 s44, 0x204
	s_movk_i32 s45, 0x5ff
	s_mov_b32 s46, s2
	s_cmp_lt_u32 s2, 0x80
	s_cbranch_scc1 .LBB0_46
	s_mov_b32 s30, s2
	s_branch .Lw0_entry
.LBB0_45:
	s_add_i32 s30, s46, s40
	s_branch .Lw0_entry

.Lw0_entry:
	s_mov_b64 s[0:1], s[38:39]
	s_load_dwordx2 s[6:7], s[0:1], 0x30
	s_load_dwordx2 s[8:9], s[0:1], 0xa0
	s_load_dwordx2 s[10:11], s[0:1], 0xa8
	s_load_dwordx2 s[12:13], s[0:1], 0x60
	s_load_dwordx2 s[14:15], s[0:1], 0x70
	s_load_dwordx2 s[16:17], s[0:1], 0xc0
	s_waitcnt lgkmcnt(0)
	v_lshrrev_b32_e32 v20, 3, v226
	v_and_b32_e32 v26, 7, v226
	v_lshlrev_b32_e32 v21, 5, v26
	v_lshlrev_b32_e32 v22, 4, v26
	v_mul_u32_u24_e32 v23, 0x104, v20
	v_add_u32_e32 v23, v23, v21
	v_mul_u32_u24_e32 v24, 0x820, v26
	v_lshl_add_u32 v24, v20, 2, v24
	s_mov_b32 s31, 1
	s_mov_b32 s37, 0
	s_cmpk_gt_u32 s30, 0x81f
	s_cbranch_scc1 .Lw0_d0_notin
	s_and_b32 s0, s30, 15
	s_lshr_b32 s1, s30, 4
	s_mul_i32 s33, s0, 0x208000
	s_lshl_b32 s34, s1, 8
	s_add_u32 s33, s33, s34
	s_add_u32 s24, s6, s33
	s_addc_u32 s25, s7, 0
	s_mov_b32 s26, 0x8200
	s_lshl_b32 s33, s1, 17
	s_lshl_b32 s34, s0, 7
	s_add_u32 s33, s33, s34
	s_add_u32 s28, s16, s33
	s_addc_u32 s29, s17, 0
	s_movk_i32 s27, 0x800
	s_branch .Lw0_d0_done
.Lw0_d0_notin:
	s_cmpk_gt_u32 s30, 0x99f
	s_cbranch_scc1 .Lw0_d0_notbr
	s_add_i32 s0, s30, 0xfffff7e0
	s_lshr_b32 s1, s0, 7
	s_and_b32 s33, s0, 7
	s_bfe_u32 s34, s0, 0x40003
	s_lshl_b32 s35, s1, 21
	s_lshl_b32 s36, s33, 18
	s_add_u32 s35, s35, s36
	s_lshl_b32 s36, s34, 8
	s_add_u32 s35, s35, s36
	s_add_u32 s24, s8, s35
	s_addc_u32 s25, s9, 0
	s_movk_i32 s26, 0x1000
	s_lshl_b32 s35, s1, 20
	s_lshl_b32 s36, s34, 16
	s_add_u32 s35, s35, s36
	s_lshl_b32 s36, s33, 7
	s_add_u32 s35, s35, s36
	s_add_u32 s35, s35, 0x1080000
	s_add_u32 s28, s16, s35
	s_addc_u32 s29, s17, 0
	s_movk_i32 s27, 0x400
	s_branch .Lw0_d0_done
.Lw0_d0_notbr:
	s_cmpk_gt_u32 s30, 0xa9f
	s_cbranch_scc1 .Lw0_d0_lora
	s_add_i32 s0, s30, 0xfffff660
	s_and_b32 s1, s0, 15
	s_lshr_b32 s33, s0, 4
	s_lshl_b32 s35, s1, 18
	s_lshl_b32 s36, s33, 8
	s_add_u32 s35, s35, s36
	s_add_u32 s24, s10, s35
	s_addc_u32 s25, s11, 0
	s_movk_i32 s26, 0x1000
	s_lshl_b32 s35, s33, 17
	s_lshl_b32 s36, s1, 7
	s_add_u32 s35, s35, s36
	s_add_u32 s35, s35, 0x1380000
	s_add_u32 s28, s16, s35
	s_addc_u32 s29, s17, 0
	s_movk_i32 s27, 0x800
	s_branch .Lw0_d0_done
.Lw0_d0_lora:
	s_add_i32 s0, s30, 0xfffff560
	s_and_b32 s1, s0, 7
	s_cmp_lt_u32 s0, 8
	s_cselect_b32 s34, s12, s14
	s_cselect_b32 s35, s13, s15
	s_mov_b32 s36, 0x1590000
	s_cselect_b32 s36, 0x1580000, s36
	s_lshl_b32 s33, s1, 8
	s_add_u32 s24, s34, s33
	s_addc_u32 s25, s35, 0
	s_movk_i32 s26, 0x800
	s_lshl_b32 s33, s1, 13
	s_add_u32 s33, s33, s36
	s_add_u32 s28, s16, s33
	s_addc_u32 s29, s17, 0
	s_movk_i32 s27, 0x80
.Lw0_d0_done:
	v_mad_u32_u24 v25, v20, s26, v21
	global_load_dwordx4 v[4:7], v25, s[24:25]
	global_load_dwordx4 v[8:11], v25, s[24:25] offset:16
	s_mov_b64 s[18:19], s[24:25]
	s_mov_b32 s20, s26
	s_mov_b64 s[22:23], s[28:29]
	s_mov_b32 s21, s27
.Lw0_A:
	s_add_i32 s30, s30, s40
	s_cmpk_lt_u32 s30, 0xab0
	s_cbranch_scc0 .Lw0_A_nonext
	s_cmpk_gt_u32 s30, 0x81f
	s_cbranch_scc1 .Lw0_d1_notin
	s_and_b32 s0, s30, 15
	s_lshr_b32 s1, s30, 4
	s_mul_i32 s33, s0, 0x208000
	s_lshl_b32 s34, s1, 8
	s_add_u32 s33, s33, s34
	s_add_u32 s24, s6, s33
	s_addc_u32 s25, s7, 0
	s_mov_b32 s26, 0x8200
	s_lshl_b32 s33, s1, 17
	s_lshl_b32 s34, s0, 7
	s_add_u32 s33, s33, s34
	s_add_u32 s28, s16, s33
	s_addc_u32 s29, s17, 0
	s_movk_i32 s27, 0x800
	s_branch .Lw0_d1_done

.Lw0_d1_done:
	v_mad_u32_u24 v25, v20, s26, v21
	global_load_dwordx4 v[12:15], v25, s[24:25]
	global_load_dwordx4 v[16:19], v25, s[24:25] offset:16
	s_cmp_lg_u32 s31, 0
	s_cbranch_scc1 .Lw0_A_w2
	s_waitcnt vmcnt(3)
	s_branch .Lw0_A_wd
.Lw0_A_w2:
	s_waitcnt vmcnt(2)
	s_branch .Lw0_A_wd
.Lw0_A_nonext:
	s_cmp_lg_u32 s31, 0
	s_cbranch_scc1 .Lw0_A_w0
	s_waitcnt vmcnt(1)
	s_branch .Lw0_A_wd

.Lw0_A_wd:
	s_mov_b32 s31, 0
	v_add_u32_e32 v26, s37, v23
	ds_write2_b32 v26, v4, v5 offset1:1
	ds_write2_b32 v26, v6, v7 offset0:2 offset1:3
	ds_write2_b32 v26, v8, v9 offset0:4 offset1:5
	ds_write2_b32 v26, v10, v11 offset0:6 offset1:7
	v_add_u32_e32 v27, s37, v24
	s_waitcnt lgkmcnt(0)
	s_barrier
	ds_read2_b32 v[28:29], v27 offset1:65
	ds_read2_b32 v[30:31], v27 offset0:130 offset1:195
	v_add_u32_e32 v26, 0x400, v27
	ds_read2_b32 v[32:33], v26 offset0:4 offset1:69
	ds_read2_b32 v[34:35], v26 offset0:134 offset1:199
	v_mad_u32_u24 v25, v20, s21, v22
	s_xor_b32 s37, s37, 0x4400
	s_waitcnt lgkmcnt(0)
	v_cvt_pk_bf16_f32 v28, v28, v29
	v_cvt_pk_bf16_f32 v29, v30, v31
	v_cvt_pk_bf16_f32 v30, v32, v33
	v_cvt_pk_bf16_f32 v31, v34, v35
	global_store_dwordx4 v25, v[28:31], s[22:23]
	s_mov_b64 s[18:19], s[24:25]
	s_mov_b32 s20, s26
	s_mov_b64 s[22:23], s[28:29]
	s_mov_b32 s21, s27
	s_cmpk_lt_u32 s30, 0xab0
	s_cbranch_scc0 .Lw0_exit

.Lw0_d2_done:
	v_mad_u32_u24 v25, v20, s26, v21
	global_load_dwordx4 v[4:7], v25, s[24:25]
	global_load_dwordx4 v[8:11], v25, s[24:25] offset:16
	s_cmp_lg_u32 s31, 0
	s_cbranch_scc1 .Lw0_B_w2
	s_waitcnt vmcnt(3)
	s_branch .Lw0_B_wd

.Lw0_B_wd:
	s_mov_b32 s31, 0
	v_add_u32_e32 v26, s37, v23
	ds_write2_b32 v26, v12, v13 offset1:1
	ds_write2_b32 v26, v14, v15 offset0:2 offset1:3
	ds_write2_b32 v26, v16, v17 offset0:4 offset1:5
	ds_write2_b32 v26, v18, v19 offset0:6 offset1:7
	v_add_u32_e32 v27, s37, v24
	s_waitcnt lgkmcnt(0)
	s_barrier
	ds_read2_b32 v[28:29], v27 offset1:65
	ds_read2_b32 v[30:31], v27 offset0:130 offset1:195
	v_add_u32_e32 v26, 0x400, v27
	ds_read2_b32 v[32:33], v26 offset0:4 offset1:69
	ds_read2_b32 v[34:35], v26 offset0:134 offset1:199
	v_mad_u32_u24 v25, v20, s21, v22
	s_xor_b32 s37, s37, 0x4400
	s_waitcnt lgkmcnt(0)
	v_cvt_pk_bf16_f32 v28, v28, v29
	v_cvt_pk_bf16_f32 v29, v30, v31
	v_cvt_pk_bf16_f32 v30, v32, v33
	v_cvt_pk_bf16_f32 v31, v34, v35
	global_store_dwordx4 v25, v[28:31], s[22:23]
	s_mov_b64 s[18:19], s[24:25]
	s_mov_b32 s20, s26
	s_mov_b64 s[22:23], s[28:29]
	s_mov_b32 s21, s27
	s_cmpk_lt_u32 s30, 0xab0
	s_cbranch_scc0 .Lw0_exit
	s_branch .Lw0_A
.Lw0_exit:
	s_barrier
	s_branch .LBB0_72

.LBB0_191:
	s_andn2_b64 vcc, exec, s[18:19]
	s_cbranch_vccnz .LBB0_222
	v_readlane_b32 s0, v254, 18
	v_readlane_b32 s1, v254, 19
	s_andn2_b64 vcc, exec, s[0:1]
	s_cbranch_vccnz .LBB0_222
	v_readlane_b32 s0, v254, 21
	v_readlane_b32 s1, v254, 22
	s_andn2_b64 vcc, exec, s[0:1]
	s_cbranch_vccnz .LBB0_222
	s_waitcnt lgkmcnt(0)
	s_add_u32 s0, s16, s56
	s_addc_u32 s1, s17, 0
	s_add_u32 s28, s0, 0x1080000
	s_addc_u32 s29, s1, 0
	s_add_u32 s16, s0, 0x1380000
	s_addc_u32 s17, s1, 0
	s_add_u32 s18, s0, 0x1580000
	s_addc_u32 s19, s1, 0
	s_add_u32 s20, s0, 0x1590000
	v_readlane_b32 s26, v255, 5
	s_addc_u32 s21, s1, 0
	v_readlane_b32 s27, v255, 6
	s_mul_i32 s23, s26, 0x2080000
	s_mov_b32 s27, s81
	s_mul_hi_u32 s22, s26, 0x2080000
	s_add_u32 s8, s8, s23
	s_addc_u32 s9, s9, s22
	s_lshl_b64 s[22:23], s[26:27], 17
	s_lshl_b64 s[24:25], s[26:27], 22
	s_mov_b32 s30, s26
	s_lshl_b64 s[26:27], s[26:27], 18
	s_add_u32 s14, s14, s22
	s_addc_u32 s15, s15, s23
	s_add_u32 s12, s12, s22
	s_addc_u32 s13, s13, s23
	s_add_u32 s6, s6, s24
	v_writelane_b32 v255, s30, 5
	s_addc_u32 s7, s7, s25
	v_readlane_b32 s22, v254, 36
	v_writelane_b32 v255, s31, 6
	s_add_u32 s30, s10, s26
	s_addc_u32 s31, s11, s27
	s_lshl_b32 s10, s22, 1
	s_add_u32 s10, s0, s10
	s_addc_u32 s11, s1, 0
	s_mov_b32 s1, s22
	v_readlane_b32 s34, v254, 20
	s_cmp_lt_u32 s34, 0x80
	s_cbranch_scc1 .LBB0_196
	s_mov_b32 s30, s34
	s_branch .Lw1_entry
.LBB0_195:
	s_add_i32 s30, s34, 0xc0
	s_branch .Lw1_entry

.Lw1_entry:
	v_readlane_b32 s0, v254, 5
	v_readlane_b32 s1, v254, 6
	s_load_dwordx2 s[6:7], s[0:1], 0x30
	s_load_dwordx2 s[8:9], s[0:1], 0xa0
	s_load_dwordx2 s[10:11], s[0:1], 0xa8
	s_load_dwordx2 s[12:13], s[0:1], 0x60
	s_load_dwordx2 s[14:15], s[0:1], 0x70
	s_load_dwordx2 s[16:17], s[0:1], 0xc0
	s_waitcnt lgkmcnt(0)
	s_add_i32 s33, s95, 1
	s_mul_i32 s34, s33, 0x2080000
	s_mul_hi_u32 s35, s33, 0x2080000
	s_add_u32 s6, s6, s34
	s_addc_u32 s7, s7, s35
	s_mul_i32 s34, s33, 0x600000
	s_add_u32 s8, s8, s34
	s_addc_u32 s9, s9, 0
	s_lshl_b32 s34, s33, 22
	s_add_u32 s10, s10, s34
	s_addc_u32 s11, s11, 0
	s_lshl_b32 s34, s33, 17
	s_add_u32 s12, s12, s34
	s_addc_u32 s13, s13, 0
	s_add_u32 s14, s14, s34
	s_addc_u32 s15, s15, 0
	s_and_b32 s34, s33, 1
	s_mul_i32 s34, s34, 0x15a0000
	s_add_u32 s16, s16, s34
	s_addc_u32 s17, s17, 0
	v_lshrrev_b32_e32 v20, 3, v226
	v_and_b32_e32 v26, 7, v226
	v_lshlrev_b32_e32 v21, 5, v26
	v_lshlrev_b32_e32 v22, 4, v26
	v_mul_u32_u24_e32 v23, 0x104, v20
	v_add_u32_e32 v23, v23, v21
	v_mul_u32_u24_e32 v24, 0x820, v26
	v_lshl_add_u32 v24, v20, 2, v24
	s_mov_b32 s31, 1
	s_mov_b32 s37, 0
	s_cmpk_gt_u32 s30, 0x81f
	s_cbranch_scc1 .Lw1_d0_notin
	s_and_b32 s0, s30, 15
	s_lshr_b32 s1, s30, 4
	s_mul_i32 s33, s0, 0x208000
	s_lshl_b32 s34, s1, 8
	s_add_u32 s33, s33, s34
	s_add_u32 s24, s6, s33
	s_addc_u32 s25, s7, 0
	s_mov_b32 s26, 0x8200
	s_lshl_b32 s33, s1, 17
	s_lshl_b32 s34, s0, 7
	s_add_u32 s33, s33, s34
	s_add_u32 s28, s16, s33
	s_addc_u32 s29, s17, 0
	s_movk_i32 s27, 0x800
	s_branch .Lw1_d0_done

.Lw1_A:
	s_add_i32 s30, s30, 0xc0
	s_cmpk_lt_u32 s30, 0xab0
	s_cbranch_scc0 .Lw1_A_nonext
	s_cmpk_gt_u32 s30, 0x81f
	s_cbranch_scc1 .Lw1_d1_notin
	s_and_b32 s0, s30, 15
	s_lshr_b32 s1, s30, 4
	s_mul_i32 s33, s0, 0x208000
	s_lshl_b32 s34, s1, 8
	s_add_u32 s33, s33, s34
	s_add_u32 s24, s6, s33
	s_addc_u32 s25, s7, 0
	s_mov_b32 s26, 0x8200
	s_lshl_b32 s33, s1, 17
	s_lshl_b32 s34, s0, 7
	s_add_u32 s33, s33, s34
	s_add_u32 s28, s16, s33
	s_addc_u32 s29, s17, 0
	s_movk_i32 s27, 0x800
	s_branch .Lw1_d1_done
